# static s_setprio 1 on the older half (waves 0-3) instead of waves 4-7
# speedup vs baseline: 1.0091x; 1.0062x over previous
; template <class Epi, class Sched, bool ALIGN_EPI = false, bool SP2 = false>
; __device__ __forceinline__ void gemm_phase(PG8_LAS unsigned char* lds, const Gemm g, const Sched& S, const Epi& E) {
;     int tid_ = threadIdx.x; asm volatile("" : "+v"(tid_));
;     const int tid = tid_, wid = __builtin_amdgcn_readfirstlane(tid >> 6), lane = tid & 63, wr = wid >> 2, wc = wid & 3, fr = lane & 15, fq = lane >> 4;
.LBB0_137:
	s_or_b64 exec, exec, s[0:1]
	s_mov_b64 s[4:5], s[78:79]
	s_mov_b64 s[0:1], s[76:77]
	v_mov_b32_e32 v8, v204
	s_setprio 0
	v_readfirstlane_b32 s98, v204
	s_lshr_b32 s98, s98, 8
	s_cmp_lg_u32 s98, 0
	s_cbranch_scc1 .Lsprio_skip_0
	s_setprio 1

; template <class Epi, class Sched, bool ALIGN_EPI = false, bool SP2 = false>
; __device__ __forceinline__ void gemm_phase(PG8_LAS unsigned char* lds, const Gemm g, const Sched& S, const Epi& E) {
;     int tid_ = threadIdx.x; asm volatile("" : "+v"(tid_));
;     const int tid = tid_, wid = __builtin_amdgcn_readfirstlane(tid >> 6), lane = tid & 63, wr = wid >> 2, wc = wid & 3, fr = lane & 15, fq = lane >> 4;
.LBB0_400:
	s_or_b64 exec, exec, s[0:1]
	s_mov_b64 s[0:1], s[78:79]
	s_mov_b64 s[4:5], s[76:77]
	v_mov_b32_e32 v8, v204
	s_setprio 0
	v_readfirstlane_b32 s98, v204
	s_lshr_b32 s98, s98, 8
	s_cmp_lg_u32 s98, 0
	s_cbranch_scc1 .Lsprio_skip_1
	s_setprio 1

; template <class Epi, class Sched, bool ALIGN_EPI = false, bool SP2 = false>
; __device__ __forceinline__ void gemm_phase(PG8_LAS unsigned char* lds, const Gemm g, const Sched& S, const Epi& E) {
;     int tid_ = threadIdx.x; asm volatile("" : "+v"(tid_));
;     const int tid = tid_, wid = __builtin_amdgcn_readfirstlane(tid >> 6), lane = tid & 63, wr = wid >> 2, wc = wid & 3, fr = lane & 15, fq = lane >> 4;
.LBB0_560:
	s_or_b64 exec, exec, s[0:1]
	s_mov_b64 s[6:7], s[78:79]
	s_mov_b64 s[0:1], s[76:77]
	v_mov_b32_e32 v8, v204
	s_setprio 0
	v_readfirstlane_b32 s98, v204
	s_lshr_b32 s98, s98, 8
	s_cmp_lg_u32 s98, 0
	s_cbranch_scc1 .Lsprio_skip_3
	s_setprio 1

; template <class Epi, class Sched, bool ALIGN_EPI = false, bool SP2 = false>
; __device__ __forceinline__ void gemm_phase(PG8_LAS unsigned char* lds, const Gemm g, const Sched& S, const Epi& E) {
;     int tid_ = threadIdx.x; asm volatile("" : "+v"(tid_));
;     const int tid = tid_, wid = __builtin_amdgcn_readfirstlane(tid >> 6), lane = tid & 63, wr = wid >> 2, wc = wid & 3, fr = lane & 15, fq = lane >> 4;
.LBB0_879:
	s_mov_b64 s[6:7], s[78:79]
	s_mov_b64 s[0:1], s[76:77]
	v_mov_b32_e32 v8, v204
	s_setprio 0
	v_readfirstlane_b32 s98, v204
	s_lshr_b32 s98, s98, 8
	s_cmp_lg_u32 s98, 0
	s_cbranch_scc1 .Lsprio_skip_7
	s_setprio 1

; template <class Epi, class Sched, bool ALIGN_EPI = false, bool SP2 = false>
; __device__ __forceinline__ void gemm_phase(PG8_LAS unsigned char* lds, const Gemm g, const Sched& S, const Epi& E) {
;     int tid_ = threadIdx.x; asm volatile("" : "+v"(tid_));
;     const int tid = tid_, wid = __builtin_amdgcn_readfirstlane(tid >> 6), lane = tid & 63, wr = wid >> 2, wc = wid & 3, fr = lane & 15, fq = lane >> 4;
.LBB0_1226:
	s_or_b64 exec, exec, s[0:1]
	s_mov_b64 s[10:11], s[78:79]
	s_mov_b64 s[0:1], s[76:77]
	v_mov_b32_e32 v8, v204
	s_setprio 0
	v_readfirstlane_b32 s98, v204
	s_lshr_b32 s98, s98, 8
	s_cmp_lg_u32 s98, 0
	s_cbranch_scc1 .Lsprio_skip_10
	s_setprio 1
